# step18: static s_setprio 1 for the younger wave half (waves 4-7) at kernel entry, on top of step16
# speedup vs baseline: 1.0058x; 1.0058x over previous
_Z4mega6Paramsii:
	v_readfirstlane_b32 s3, v0
	s_nop 3
	s_and_b32 s3, s3, 0x3ff
	s_lshr_b32 s3, s3, 6
	s_cmp_ge_u32 s3, 4
	s_cbranch_scc0 .Lprio_done
	s_setprio 1
.Lprio_done:
	s_load_dwordx16 s[8:23], s[0:1], 0x0
	s_load_dwordx16 s[52:67], s[0:1], 0x40
	s_load_dwordx16 s[68:83], s[0:1], 0x80
	s_load_dwordx16 s[36:51], s[0:1], 0xc0
	s_load_dwordx2 s[90:91], s[0:1], 0x130
	s_load_dwordx4 s[84:87], s[0:1], 0x120
	s_load_dwordx8 s[24:31], s[0:1], 0x100
	s_add_u32 s4, s0, 0x138
	s_addc_u32 s5, s1, 0
	s_load_dword s33, s[0:1], 0x138
	s_waitcnt lgkmcnt(0)
	s_cmp_gt_i32 s90, 0
	v_writelane_b32 v252, s4, 0
	s_cselect_b64 s[0:1], -1, 0
	s_cmp_lt_i32 s91, 1
	v_writelane_b32 v252, s5, 1
	s_cselect_b64 s[4:5], -1, 0
	s_or_b64 s[4:5], s[0:1], s[4:5]
	s_and_b64 vcc, exec, s[4:5]
	s_cbranch_vccnz .LBB0_79
	s_cmp_lt_i32 s90, 0
	s_cbranch_scc1 .LBB0_3
	v_and_b32_e32 v2, 0x3ff, v0
	s_cbranch_execz .LBB0_4
	s_branch .LBB0_24
